# v114 + norm phase wave stagger: waves start (wave&3)*8*64 clocks apart so load bursts and reduce/store stretches of different waves overlap
# speedup vs baseline: 1.0086x; 1.0058x over previous
; __device__ __forceinline__ void p_norm(const Args& a, int l, int lane, int wave, int bid, int G) {
;     const int gw = bid * 8 + wave, NGW = G * 8;
;     const float* mod = (const float*)(a.ws + WS_MOD) + (size_t)l * NMOD * 3072;
;     const float* g = a.in[9] + (size_t)l * D;
;     bf16_t* H = (bf16_t*)(a.ws + WS_H);
;     const bf16_t* X = (const bf16_t*)(a.ws + (l == 0 ? WS_XB0 : WS_XB));
;     ...
; #pragma unroll 1
;     for (int n = 0; n < NPB; ++n) {
;         const float* mp = mod + (size_t)n * 3072;
;         f32x4 gs[4], sh[4];
; #pragma unroll
;         for (int j = 0; j < 4; ++j) { gs[j] = *((const f32x4*)g + 64 * j + lane) * (*((const f32x4*)(mp + D) + 64 * j + lane) + 1.0f); sh[j] = *((const f32x4*)mp + 64 * j + lane); }
; #pragma unroll 1
;         for (int r0 = gw; r0 < LP; r0 += 3 * NGW) {
.LBB0_191:
	s_xor_b64 s[0:1], s[4:5], -1
	v_writelane_b32 v255, s0, 8
	v_mov_b32_e32 v0, v208
	s_mul_i32 s2, s66, 0x18c000
	v_writelane_b32 v255, s1, 9
	v_readfirstlane_b32 s0, v0
	s_ashr_i32 s0, s0, 6
	v_readlane_b32 s1, v254, 6
	s_add_i32 s0, s0, s1
	v_readlane_b32 s1, v253, 36
	v_readlane_b32 s8, v253, 20
	s_mov_b32 s67, s87
	v_writelane_b32 v255, s2, 10
	s_add_u32 s2, s1, s2
	v_readlane_b32 s1, v253, 37
	v_readlane_b32 s10, v253, 22
	v_readlane_b32 s11, v253, 23
	s_addc_u32 s3, s1, 0
	s_mov_b64 s[28:29], s[4:5]
	s_lshl_b64 s[4:5], s[66:67], 12
	s_mov_b64 s[6:7], s[10:11]
	s_add_u32 s6, s6, s4
	s_addc_u32 s7, s7, s5
	v_writelane_b32 v255, s28, 11
	s_and_b64 s[4:5], s[28:29], exec
	s_mov_b32 s1, 0xcc00000
	s_cselect_b32 s4, s1, 0xaa00000
	v_and_b32_e32 v50, 63, v0
	v_readlane_b32 s9, v253, 21
	s_add_u32 s8, s78, s4
	v_readlane_b32 s12, v253, 24
	v_readlane_b32 s13, v253, 25
	v_readlane_b32 s14, v253, 26
	v_readlane_b32 s15, v253, 27
	v_readlane_b32 s16, v253, 28
	v_readlane_b32 s17, v253, 29
	s_addc_u32 s9, s79, 0
	v_lshlrev_b32_e32 v172, 4, v50
	v_readlane_b32 s18, v253, 30
	v_readlane_b32 s19, v253, 31
	v_readlane_b32 s20, v253, 32
	v_readlane_b32 s21, v253, 33
	s_mov_b64 s[12:13], s[16:17]
	v_lshl_add_u64 v[48:49], s[6:7], 0, v[172:173]
	s_cmpk_lt_i32 s0, 0x1000
	v_lshlrev_b32_e32 v172, 3, v50
	s_movk_i32 s24, 0x1000
	s_mov_b64 s[14:15], s[18:19]
	s_mov_b64 s[16:17], s[20:21]
	v_writelane_b32 v255, s29, 12
	s_mov_b32 s5, s87
	v_lshl_add_u64 v[52:53], s[46:47], 0, v[172:173]
	v_lshl_add_u64 v[54:55], s[8:9], 0, v[172:173]
	s_cselect_b64 s[6:7], -1, 0
	v_lshlrev_b32_e32 v172, 4, v50
	s_mov_b32 s1, s43
	s_mov_b32 s18, s44
	s_mov_b32 s19, s87
	s_mov_b32 s20, s87
	v_readlane_b32 s22, v253, 34
	v_readlane_b32 s23, v253, 35
	v_readfirstlane_b32 s8, v208
	s_nop 3
	s_bfe_u32 s8, s8, 0x20006
	s_cmp_eq_u32 s8, 0
	s_cbranch_scc1 .Lnst_go
	s_cmp_eq_u32 s8, 1
	s_cbranch_scc1 .Lnst_1
	s_cmp_eq_u32 s8, 2
	s_cbranch_scc1 .Lnst_2
	s_sleep 24
	s_branch .Lnst_go
.Lnst_2:
	s_sleep 16
	s_branch .Lnst_go
.Lnst_1:
	s_sleep 8
.Lnst_go:
	s_branch .LBB0_193
.LBB0_192:
	s_add_i32 s20, s20, 1
	s_addk_i32 s19, 0x1000
	s_addk_i32 s18, 0x1000
	s_addk_i32 s1, 0x1000
	s_cmp_eq_u32 s20, 4
	s_cbranch_scc1 .LBB0_204
